# noprio + scan-unit state MFMA chain: transposed fragments prefetched two k-steps ahead with counted lgkmcnt waits
# speedup vs baseline: 1.0182x; 1.0082x over previous
; #define LAS __attribute__((address_space(3)))
; __device__ __forceinline__ s16x8 tr_frag(LAS const char* img, int half_bytes, int nb, int ks, int lane) {
;     LAS const char* p = img + nb * half_bytes + (16 * ks + 8 * (lane >> 5) + ((lane & 15) >> 2)) * 64 + (16 * ((lane >> 4) & 1) + 4 * (lane & 3)) * 2;
;     const s16x4 lo = __builtin_bit_cast(s16x4, __builtin_amdgcn_ds_read_tr16_b64_v4i16((LAS v4i16_t*)p));
;     const s16x4 hi = __builtin_bit_cast(s16x4, __builtin_amdgcn_ds_read_tr16_b64_v4i16((LAS v4i16_t*)(p + 256)));
;     return (s16x8){lo[0], lo[1], lo[2], lo[3], hi[0], hi[1], hi[2], hi[3]};
; }
.LBB0_271:
	s_add_i32 s83, s23, s75
	v_lshl_add_u64 v[6:7], s[12:13], 0, v[108:109]
	s_add_i32 s12, s83, 0x12400
	s_waitcnt lgkmcnt(0)
	s_barrier
	v_add_u32_e32 v140, s18, v108
	v_mov_b32_e32 v0, s12
	ds_read_b128 v[2:5], v140
	ds_read_b32 v141, v0
	s_add_i32 s12, s83, 0x12480
	v_mov_b32_e32 v0, s12
	ds_read_b32 v0, v0
	s_waitcnt lgkmcnt(2)
	global_store_dwordx4 v[6:7], v[2:5], off
	s_and_b64 vcc, exec, s[6:7]
	s_waitcnt lgkmcnt(1)
	v_max_f32_e32 v2, v141, v141
	v_max_f32_e32 v3, v111, v111
	v_max_f32_e32 v139, v3, v2
	s_cbranch_vccnz .LBB0_289
	v_add_u32_e32 v142, v128, v129
	v_add_u32_e32 v143, v134, v129
	s_waitcnt vmcnt(3)
	ds_read_b64_tr_b16 v[18:19], v142
	ds_read_b64_tr_b16 v[20:21], v142 offset:256
	ds_read_b64_tr_b16 v[98:99], v143 offset:32768
	ds_read_b64_tr_b16 v[100:101], v143 offset:33024
	ds_read_b64_tr_b16 v[152:153], v142 offset:1024
	ds_read_b64_tr_b16 v[154:155], v142 offset:1280
	ds_read_b64_tr_b16 v[156:157], v143 offset:33792
	ds_read_b64_tr_b16 v[158:159], v143 offset:34048
	ds_read_b64_tr_b16 v[160:161], v142 offset:2048
	ds_read_b64_tr_b16 v[162:163], v142 offset:2304
	ds_read_b64_tr_b16 v[164:165], v143 offset:34816
	ds_read_b64_tr_b16 v[166:167], v143 offset:35072
	s_mov_b32 s41, s40
	s_mov_b32 s42, s40
	s_mov_b32 s43, s40
	s_waitcnt vmcnt(1) lgkmcnt(8)
	v_mfma_f32_32x32x16_f16 v[18:33], v[18:21], v[98:101], 0
	s_mov_b32 s44, s40
	s_mov_b32 s45, s40
	s_mov_b32 s46, s40
	s_mov_b32 s47, s40
	s_mov_b32 s48, s40
	s_mov_b32 s49, s40
	s_mov_b32 s50, s40
	s_mov_b32 s51, s40
	s_mov_b32 s52, s40
	s_mov_b32 s53, s40
	s_mov_b32 s54, s40
	s_mov_b32 s55, s40
	v_mov_b64_e32 v[2:3], s[40:41]
	v_mov_b64_e32 v[4:5], s[42:43]
	v_mov_b64_e32 v[6:7], s[44:45]
	v_mov_b64_e32 v[8:9], s[46:47]
	v_mov_b64_e32 v[10:11], s[48:49]
	v_mov_b64_e32 v[12:13], s[50:51]
	v_mov_b64_e32 v[14:15], s[52:53]
	v_mov_b64_e32 v[16:17], s[54:55]
	s_and_b64 vcc, exec, s[4:5]
	s_cbranch_vccnz .LBB0_274
	v_mov_b32_e32 v131, v130
	v_mov_b32_e32 v132, v130
	v_mov_b32_e32 v133, v130
	s_nop 1
	v_mfma_f32_32x32x16_f16 v[2:17], v[130:133], v[98:101], 0
.LBB0_274:
	ds_read_b64_tr_b16 v[144:145], v142 offset:3072
	ds_read_b64_tr_b16 v[146:147], v142 offset:3328
	ds_read_b64_tr_b16 v[98:99], v143 offset:35840
	ds_read_b64_tr_b16 v[100:101], v143 offset:36096
	s_and_b64 vcc, exec, s[4:5]
	s_waitcnt lgkmcnt(8)
	v_mfma_f32_32x32x16_f16 v[18:33], v[152:155], v[156:159], v[18:33]
	s_cbranch_vccnz .LBB0_276
	v_mov_b32_e32 v131, v130
	v_mov_b32_e32 v132, v130
	v_mov_b32_e32 v133, v130
	s_nop 1
	v_mfma_f32_32x32x16_f16 v[2:17], v[130:133], v[156:159], v[2:17]
.LBB0_276:
	ds_read_b64_tr_b16 v[152:153], v142 offset:4096
	ds_read_b64_tr_b16 v[154:155], v142 offset:4352
	ds_read_b64_tr_b16 v[156:157], v143 offset:36864
	ds_read_b64_tr_b16 v[158:159], v143 offset:37120
	s_and_b64 vcc, exec, s[4:5]
	s_waitcnt lgkmcnt(8)
	v_mfma_f32_32x32x16_f16 v[18:33], v[160:163], v[164:167], v[18:33]
	s_cbranch_vccnz .LBB0_278
	v_mov_b32_e32 v131, v130
	v_mov_b32_e32 v132, v130
	v_mov_b32_e32 v133, v130
	s_nop 1
	v_mfma_f32_32x32x16_f16 v[2:17], v[130:133], v[164:167], v[2:17]
.LBB0_278:
	ds_read_b64_tr_b16 v[160:161], v142 offset:5120
	ds_read_b64_tr_b16 v[162:163], v142 offset:5376
	ds_read_b64_tr_b16 v[164:165], v143 offset:37888
	ds_read_b64_tr_b16 v[166:167], v143 offset:38144
	s_and_b64 vcc, exec, s[4:5]
	s_waitcnt lgkmcnt(8)
	v_mfma_f32_32x32x16_f16 v[18:33], v[144:147], v[98:101], v[18:33]
	s_cbranch_vccnz .LBB0_280
	v_mov_b32_e32 v131, v130
	v_mov_b32_e32 v132, v130
	v_mov_b32_e32 v133, v130
	s_nop 1
	v_mfma_f32_32x32x16_f16 v[2:17], v[130:133], v[98:101], v[2:17]
.LBB0_280:
	ds_read_b64_tr_b16 v[144:145], v142 offset:6144
	ds_read_b64_tr_b16 v[146:147], v142 offset:6400
	ds_read_b64_tr_b16 v[98:99], v143 offset:38912
	ds_read_b64_tr_b16 v[100:101], v143 offset:39168
	s_and_b64 vcc, exec, s[4:5]
	s_waitcnt lgkmcnt(8)
	v_mfma_f32_32x32x16_f16 v[18:33], v[152:155], v[156:159], v[18:33]
	s_cbranch_vccnz .LBB0_282
	v_mov_b32_e32 v131, v130
	v_mov_b32_e32 v132, v130
	v_mov_b32_e32 v133, v130
	s_nop 1
	v_mfma_f32_32x32x16_f16 v[2:17], v[130:133], v[156:159], v[2:17]
.LBB0_282:
	ds_read_b64_tr_b16 v[152:153], v142 offset:7168
	ds_read_b64_tr_b16 v[154:155], v142 offset:7424
	ds_read_b64_tr_b16 v[156:157], v143 offset:39936
	ds_read_b64_tr_b16 v[158:159], v143 offset:40192
	s_and_b64 vcc, exec, s[4:5]
	s_waitcnt lgkmcnt(8)
	v_mfma_f32_32x32x16_f16 v[18:33], v[160:163], v[164:167], v[18:33]
	s_cbranch_vccnz .LBB0_284
	v_mov_b32_e32 v131, v130
	v_mov_b32_e32 v132, v130
	v_mov_b32_e32 v133, v130
	s_nop 1
	v_mfma_f32_32x32x16_f16 v[2:17], v[130:133], v[164:167], v[2:17]
.LBB0_284:
	s_and_b64 vcc, exec, s[4:5]
	s_waitcnt lgkmcnt(4)
	v_mfma_f32_32x32x16_f16 v[18:33], v[144:147], v[98:101], v[18:33]
	s_cbranch_vccnz .LBB0_286
	v_mov_b32_e32 v131, v130
	v_mov_b32_e32 v132, v130
	v_mov_b32_e32 v133, v130
	s_nop 1
	v_mfma_f32_32x32x16_f16 v[2:17], v[130:133], v[98:101], v[2:17]
.LBB0_286:
	s_and_b64 vcc, exec, s[4:5]
	s_waitcnt lgkmcnt(0)
	v_mfma_f32_32x32x16_f16 v[18:33], v[152:155], v[156:159], v[18:33]
	s_cbranch_vccnz .LBB0_288
	v_mov_b32_e32 v131, v130
	v_mov_b32_e32 v132, v130
	v_mov_b32_e32 v133, v130
	s_nop 1
	v_mfma_f32_32x32x16_f16 v[2:17], v[130:133], v[156:159], v[2:17]

; #define LAS __attribute__((address_space(3)))
; __device__ __forceinline__ s16x8 tr_frag(LAS const char* img, int half_bytes, int nb, int ks, int lane) {
;     LAS const char* p = img + nb * half_bytes + (16 * ks + 8 * (lane >> 5) + ((lane & 15) >> 2)) * 64 + (16 * ((lane >> 4) & 1) + 4 * (lane & 3)) * 2;
;     const s16x4 lo = __builtin_bit_cast(s16x4, __builtin_amdgcn_ds_read_tr16_b64_v4i16((LAS v4i16_t*)p));
;     const s16x4 hi = __builtin_bit_cast(s16x4, __builtin_amdgcn_ds_read_tr16_b64_v4i16((LAS v4i16_t*)(p + 256)));
;     return (s16x8){lo[0], lo[1], lo[2], lo[3], hi[0], hi[1], hi[2], hi[3]};
; }
.LBB0_300:
	v_add_u32_e32 v143, v128, v129
	v_add_u32_e32 v144, v134, v129
	ds_read_b64_tr_b16 v[18:19], v143 offset:16384
	ds_read_b64_tr_b16 v[20:21], v143 offset:16640
	ds_read_b64_tr_b16 v[98:99], v144 offset:49152
	ds_read_b64_tr_b16 v[100:101], v144 offset:49408
	ds_read_b64_tr_b16 v[152:153], v143 offset:17408
	ds_read_b64_tr_b16 v[154:155], v143 offset:17664
	ds_read_b64_tr_b16 v[156:157], v144 offset:50176
	ds_read_b64_tr_b16 v[158:159], v144 offset:50432
	ds_read_b64_tr_b16 v[160:161], v143 offset:18432
	ds_read_b64_tr_b16 v[162:163], v143 offset:18688
	ds_read_b64_tr_b16 v[164:165], v144 offset:51200
	ds_read_b64_tr_b16 v[166:167], v144 offset:51456
	s_mov_b32 s41, s40
	s_mov_b32 s42, s40
	s_mov_b32 s43, s40
	s_waitcnt vmcnt(2) lgkmcnt(8)
	v_mfma_f32_32x32x16_f16 v[18:33], v[18:21], v[98:101], 0
	s_mov_b32 s44, s40
	s_mov_b32 s45, s40
	s_mov_b32 s46, s40
	s_mov_b32 s47, s40
	s_mov_b32 s48, s40
	s_mov_b32 s49, s40
	s_mov_b32 s50, s40
	s_mov_b32 s51, s40
	s_mov_b32 s52, s40
	s_mov_b32 s53, s40
	s_mov_b32 s54, s40
	s_mov_b32 s55, s40
	v_mov_b64_e32 v[2:3], s[40:41]
	v_mov_b64_e32 v[4:5], s[42:43]
	v_mov_b64_e32 v[6:7], s[44:45]
	v_mov_b64_e32 v[8:9], s[46:47]
	v_mov_b64_e32 v[10:11], s[48:49]
	v_mov_b64_e32 v[12:13], s[50:51]
	v_mov_b64_e32 v[14:15], s[52:53]
	v_mov_b64_e32 v[16:17], s[54:55]
	s_and_b64 vcc, exec, s[4:5]
	s_cbranch_vccnz .LBB0_302
	v_mov_b32_e32 v131, v130
	v_mov_b32_e32 v132, v130
	v_mov_b32_e32 v133, v130
	s_nop 1
	v_mfma_f32_32x32x16_f16 v[2:17], v[130:133], v[98:101], 0
.LBB0_302:
	ds_read_b64_tr_b16 v[146:147], v143 offset:19456
	ds_read_b64_tr_b16 v[148:149], v143 offset:19712
	ds_read_b64_tr_b16 v[98:99], v144 offset:52224
	ds_read_b64_tr_b16 v[100:101], v144 offset:52480
	s_and_b64 vcc, exec, s[4:5]
	s_waitcnt lgkmcnt(8)
	v_mfma_f32_32x32x16_f16 v[18:33], v[152:155], v[156:159], v[18:33]
	s_cbranch_vccnz .LBB0_304
	v_mov_b32_e32 v131, v130
	v_mov_b32_e32 v132, v130
	v_mov_b32_e32 v133, v130
	s_nop 1
	v_mfma_f32_32x32x16_f16 v[2:17], v[130:133], v[156:159], v[2:17]
.LBB0_304:
	ds_read_b64_tr_b16 v[152:153], v143 offset:20480
	ds_read_b64_tr_b16 v[154:155], v143 offset:20736
	ds_read_b64_tr_b16 v[156:157], v144 offset:53248
	ds_read_b64_tr_b16 v[158:159], v144 offset:53504
	s_and_b64 vcc, exec, s[4:5]
	s_waitcnt lgkmcnt(8)
	v_mfma_f32_32x32x16_f16 v[18:33], v[160:163], v[164:167], v[18:33]
	s_cbranch_vccnz .LBB0_306
	v_mov_b32_e32 v131, v130
	v_mov_b32_e32 v132, v130
	v_mov_b32_e32 v133, v130
	s_nop 1
	v_mfma_f32_32x32x16_f16 v[2:17], v[130:133], v[164:167], v[2:17]
.LBB0_306:
	ds_read_b64_tr_b16 v[160:161], v143 offset:21504
	ds_read_b64_tr_b16 v[162:163], v143 offset:21760
	ds_read_b64_tr_b16 v[164:165], v144 offset:54272
	ds_read_b64_tr_b16 v[166:167], v144 offset:54528
	s_and_b64 vcc, exec, s[4:5]
	s_waitcnt lgkmcnt(8)
	v_mfma_f32_32x32x16_f16 v[18:33], v[146:149], v[98:101], v[18:33]
	s_cbranch_vccnz .LBB0_308
	v_mov_b32_e32 v131, v130
	v_mov_b32_e32 v132, v130
	v_mov_b32_e32 v133, v130
	s_nop 1
	v_mfma_f32_32x32x16_f16 v[2:17], v[130:133], v[98:101], v[2:17]
.LBB0_308:
	ds_read_b64_tr_b16 v[146:147], v143 offset:22528
	ds_read_b64_tr_b16 v[148:149], v143 offset:22784
	ds_read_b64_tr_b16 v[98:99], v144 offset:55296
	ds_read_b64_tr_b16 v[100:101], v144 offset:55552
	s_and_b64 vcc, exec, s[4:5]
	s_waitcnt lgkmcnt(8)
	v_mfma_f32_32x32x16_f16 v[18:33], v[152:155], v[156:159], v[18:33]
	s_cbranch_vccnz .LBB0_310
	v_mov_b32_e32 v131, v130
	v_mov_b32_e32 v132, v130
	v_mov_b32_e32 v133, v130
	s_nop 1
	v_mfma_f32_32x32x16_f16 v[2:17], v[130:133], v[156:159], v[2:17]
.LBB0_310:
	ds_read_b64_tr_b16 v[152:153], v143 offset:23552
	ds_read_b64_tr_b16 v[154:155], v143 offset:23808
	ds_read_b64_tr_b16 v[156:157], v144 offset:56320
	ds_read_b64_tr_b16 v[158:159], v144 offset:56576
	s_and_b64 vcc, exec, s[4:5]
	s_waitcnt lgkmcnt(8)
	v_mfma_f32_32x32x16_f16 v[18:33], v[160:163], v[164:167], v[18:33]
	s_cbranch_vccnz .LBB0_312
	v_mov_b32_e32 v131, v130
	v_mov_b32_e32 v132, v130
	v_mov_b32_e32 v133, v130
	s_nop 1
	v_mfma_f32_32x32x16_f16 v[2:17], v[130:133], v[164:167], v[2:17]
.LBB0_312:
	s_and_b64 vcc, exec, s[4:5]
	s_waitcnt lgkmcnt(4)
	v_mfma_f32_32x32x16_f16 v[18:33], v[146:149], v[98:101], v[18:33]
	s_cbranch_vccnz .LBB0_314
	v_mov_b32_e32 v131, v130
	v_mov_b32_e32 v132, v130
	v_mov_b32_e32 v133, v130
	s_nop 1
	v_mfma_f32_32x32x16_f16 v[2:17], v[130:133], v[98:101], v[2:17]

.LBB0_325:
	v_lshl_add_u64 v[6:7], s[12:13], 0, v[108:109]
	s_add_i32 s12, s83, 0x12408
	s_waitcnt lgkmcnt(0)
	s_barrier
	v_mov_b32_e32 v0, s12
	ds_read_b128 v[2:5], v140
	ds_read_b32 v141, v0
	s_add_i32 s12, s83, 0x12488
	v_mov_b32_e32 v0, s12
	ds_read_b32 v0, v0
	s_waitcnt lgkmcnt(2)
	global_store_dwordx4 v[6:7], v[2:5], off
	s_and_b64 vcc, exec, s[6:7]
	s_waitcnt lgkmcnt(1)
	v_max_f32_e32 v2, v141, v141
	v_max_f32_e32 v3, v111, v111
	v_max_f32_e32 v140, v3, v2
	s_cbranch_vccnz .LBB0_343
	v_add_u32_e32 v142, v128, v129
	v_add_u32_e32 v143, v134, v129
	ds_read_b64_tr_b16 v[18:19], v142
	ds_read_b64_tr_b16 v[20:21], v142 offset:256
	ds_read_b64_tr_b16 v[98:99], v143 offset:32768
	ds_read_b64_tr_b16 v[100:101], v143 offset:33024
	ds_read_b64_tr_b16 v[152:153], v142 offset:1024
	ds_read_b64_tr_b16 v[154:155], v142 offset:1280
	ds_read_b64_tr_b16 v[156:157], v143 offset:33792
	ds_read_b64_tr_b16 v[158:159], v143 offset:34048
	ds_read_b64_tr_b16 v[160:161], v142 offset:2048
	ds_read_b64_tr_b16 v[162:163], v142 offset:2304
	ds_read_b64_tr_b16 v[164:165], v143 offset:34816
	ds_read_b64_tr_b16 v[166:167], v143 offset:35072
	s_mov_b32 s41, s40
	s_mov_b32 s42, s40
	s_mov_b32 s43, s40
	s_waitcnt vmcnt(3) lgkmcnt(8)
	v_mfma_f32_32x32x16_f16 v[18:33], v[18:21], v[98:101], 0
	s_mov_b32 s44, s40
	s_mov_b32 s45, s40
	s_mov_b32 s46, s40
	s_mov_b32 s47, s40
	s_mov_b32 s48, s40
	s_mov_b32 s49, s40
	s_mov_b32 s50, s40
	s_mov_b32 s51, s40
	s_mov_b32 s52, s40
	s_mov_b32 s53, s40
	s_mov_b32 s54, s40
	s_mov_b32 s55, s40
	v_mov_b64_e32 v[2:3], s[40:41]
	v_mov_b64_e32 v[4:5], s[42:43]
	v_mov_b64_e32 v[6:7], s[44:45]
	v_mov_b64_e32 v[8:9], s[46:47]
	v_mov_b64_e32 v[10:11], s[48:49]
	v_mov_b64_e32 v[12:13], s[50:51]
	v_mov_b64_e32 v[14:15], s[52:53]
	v_mov_b64_e32 v[16:17], s[54:55]
	s_and_b64 vcc, exec, s[4:5]
	s_cbranch_vccnz .LBB0_328
	v_mov_b32_e32 v131, v130
	v_mov_b32_e32 v132, v130
	v_mov_b32_e32 v133, v130
	s_nop 1
	v_mfma_f32_32x32x16_f16 v[2:17], v[130:133], v[98:101], 0

; #define LAS __attribute__((address_space(3)))
; __device__ __forceinline__ s16x8 tr_frag(LAS const char* img, int half_bytes, int nb, int ks, int lane) {
;     LAS const char* p = img + nb * half_bytes + (16 * ks + 8 * (lane >> 5) + ((lane & 15) >> 2)) * 64 + (16 * ((lane >> 4) & 1) + 4 * (lane & 3)) * 2;
;     const s16x4 lo = __builtin_bit_cast(s16x4, __builtin_amdgcn_ds_read_tr16_b64_v4i16((LAS v4i16_t*)p));
;     const s16x4 hi = __builtin_bit_cast(s16x4, __builtin_amdgcn_ds_read_tr16_b64_v4i16((LAS v4i16_t*)(p + 256)));
;     return (s16x8){lo[0], lo[1], lo[2], lo[3], hi[0], hi[1], hi[2], hi[3]};
; }
.LBB0_352:
	v_lshl_add_u64 v[6:7], s[12:13], 0, v[108:109]
	s_add_i32 s12, s83, 0x1240c
	s_waitcnt lgkmcnt(0)
	s_barrier
	v_mov_b32_e32 v0, s12
	ds_read_b128 v[2:5], v139
	ds_read_b32 v139, v0
	s_add_i32 s12, s83, 0x1248c
	v_mov_b32_e32 v0, s12
	ds_read_b32 v0, v0
	s_waitcnt lgkmcnt(2)
	global_store_dwordx4 v[6:7], v[2:5], off
	s_and_b64 vcc, exec, s[6:7]
	s_waitcnt lgkmcnt(1)
	v_max_f32_e32 v2, v139, v139
	v_max_f32_e32 v3, v111, v111
	v_max_f32_e32 v138, v3, v2
	s_cbranch_vccnz .LBB0_261
	v_add_u32_e32 v140, v128, v129
	v_add_u32_e32 v141, v134, v129
	ds_read_b64_tr_b16 v[18:19], v140 offset:16384
	ds_read_b64_tr_b16 v[20:21], v140 offset:16640
	ds_read_b64_tr_b16 v[98:99], v141 offset:49152
	ds_read_b64_tr_b16 v[100:101], v141 offset:49408
	ds_read_b64_tr_b16 v[152:153], v140 offset:17408
	ds_read_b64_tr_b16 v[154:155], v140 offset:17664
	ds_read_b64_tr_b16 v[156:157], v141 offset:50176
	ds_read_b64_tr_b16 v[158:159], v141 offset:50432
	ds_read_b64_tr_b16 v[160:161], v140 offset:18432
	ds_read_b64_tr_b16 v[162:163], v140 offset:18688
	ds_read_b64_tr_b16 v[164:165], v141 offset:51200
	ds_read_b64_tr_b16 v[166:167], v141 offset:51456
	s_mov_b32 s41, s40
	s_mov_b32 s42, s40
	s_mov_b32 s43, s40
	s_waitcnt lgkmcnt(8)
	v_mfma_f32_32x32x16_f16 v[18:33], v[18:21], v[98:101], 0
	s_mov_b32 s44, s40
	s_mov_b32 s45, s40
	s_mov_b32 s46, s40
	s_mov_b32 s47, s40
	s_mov_b32 s48, s40
	s_mov_b32 s49, s40
	s_mov_b32 s50, s40
	s_mov_b32 s51, s40
	s_mov_b32 s52, s40
	s_mov_b32 s53, s40
	s_mov_b32 s54, s40
	s_mov_b32 s55, s40
	v_mov_b64_e32 v[2:3], s[40:41]
	v_mov_b64_e32 v[4:5], s[42:43]
	v_mov_b64_e32 v[6:7], s[44:45]
	v_mov_b64_e32 v[8:9], s[46:47]
	v_mov_b64_e32 v[10:11], s[48:49]
	v_mov_b64_e32 v[12:13], s[50:51]
	v_mov_b64_e32 v[14:15], s[52:53]
	v_mov_b64_e32 v[16:17], s[54:55]
	s_and_b64 vcc, exec, s[4:5]
	s_cbranch_vccnz .LBB0_355
	v_mov_b32_e32 v131, v130
	v_mov_b32_e32 v132, v130
	v_mov_b32_e32 v133, v130
	s_nop 1
	v_mfma_f32_32x32x16_f16 v[2:17], v[130:133], v[98:101], 0
.LBB0_355:
	ds_read_b64_tr_b16 v[142:143], v140 offset:19456
	ds_read_b64_tr_b16 v[144:145], v140 offset:19712
	ds_read_b64_tr_b16 v[98:99], v141 offset:52224
	ds_read_b64_tr_b16 v[100:101], v141 offset:52480
	s_and_b64 vcc, exec, s[4:5]
	s_waitcnt lgkmcnt(8)
	v_mfma_f32_32x32x16_f16 v[18:33], v[152:155], v[156:159], v[18:33]
	s_cbranch_vccnz .LBB0_357
	v_mov_b32_e32 v131, v130
	v_mov_b32_e32 v132, v130
	v_mov_b32_e32 v133, v130
	s_nop 1
	v_mfma_f32_32x32x16_f16 v[2:17], v[130:133], v[156:159], v[2:17]
.LBB0_357:
	ds_read_b64_tr_b16 v[152:153], v140 offset:20480
	ds_read_b64_tr_b16 v[154:155], v140 offset:20736
	ds_read_b64_tr_b16 v[156:157], v141 offset:53248
	ds_read_b64_tr_b16 v[158:159], v141 offset:53504
	s_and_b64 vcc, exec, s[4:5]
	s_waitcnt lgkmcnt(8)
	v_mfma_f32_32x32x16_f16 v[18:33], v[160:163], v[164:167], v[18:33]
	s_cbranch_vccnz .LBB0_359
	v_mov_b32_e32 v131, v130
	v_mov_b32_e32 v132, v130
	v_mov_b32_e32 v133, v130
	s_nop 1
	v_mfma_f32_32x32x16_f16 v[2:17], v[130:133], v[164:167], v[2:17]
.LBB0_359:
	ds_read_b64_tr_b16 v[160:161], v140 offset:21504
	ds_read_b64_tr_b16 v[162:163], v140 offset:21760
	ds_read_b64_tr_b16 v[164:165], v141 offset:54272
	ds_read_b64_tr_b16 v[166:167], v141 offset:54528
	s_and_b64 vcc, exec, s[4:5]
	s_waitcnt lgkmcnt(8)
	v_mfma_f32_32x32x16_f16 v[18:33], v[142:145], v[98:101], v[18:33]
	s_cbranch_vccnz .LBB0_361
	v_mov_b32_e32 v131, v130
	v_mov_b32_e32 v132, v130
	v_mov_b32_e32 v133, v130
	s_nop 1
	v_mfma_f32_32x32x16_f16 v[2:17], v[130:133], v[98:101], v[2:17]
.LBB0_361:
	ds_read_b64_tr_b16 v[142:143], v140 offset:22528
	ds_read_b64_tr_b16 v[144:145], v140 offset:22784
	ds_read_b64_tr_b16 v[98:99], v141 offset:55296
	ds_read_b64_tr_b16 v[100:101], v141 offset:55552
	s_and_b64 vcc, exec, s[4:5]
	s_waitcnt lgkmcnt(8)
	v_mfma_f32_32x32x16_f16 v[18:33], v[152:155], v[156:159], v[18:33]
	s_cbranch_vccnz .LBB0_363
	v_mov_b32_e32 v131, v130
	v_mov_b32_e32 v132, v130
	v_mov_b32_e32 v133, v130
	s_nop 1
	v_mfma_f32_32x32x16_f16 v[2:17], v[130:133], v[156:159], v[2:17]
.LBB0_363:
	ds_read_b64_tr_b16 v[152:153], v140 offset:23552
	ds_read_b64_tr_b16 v[154:155], v140 offset:23808
	ds_read_b64_tr_b16 v[156:157], v141 offset:56320
	ds_read_b64_tr_b16 v[158:159], v141 offset:56576
	s_and_b64 vcc, exec, s[4:5]
	s_waitcnt lgkmcnt(8)
	v_mfma_f32_32x32x16_f16 v[18:33], v[160:163], v[164:167], v[18:33]
	s_cbranch_vccnz .LBB0_365
	v_mov_b32_e32 v131, v130
	v_mov_b32_e32 v132, v130
	v_mov_b32_e32 v133, v130
	s_nop 1
	v_mfma_f32_32x32x16_f16 v[2:17], v[130:133], v[164:167], v[2:17]
.LBB0_365:
	s_and_b64 vcc, exec, s[4:5]
	s_waitcnt lgkmcnt(4)
	v_mfma_f32_32x32x16_f16 v[18:33], v[142:145], v[98:101], v[18:33]
	s_cbranch_vccnz .LBB0_367
	v_mov_b32_e32 v131, v130
	v_mov_b32_e32 v132, v130
	v_mov_b32_e32 v133, v130
	s_nop 1
	v_mfma_f32_32x32x16_f16 v[2:17], v[130:133], v[98:101], v[2:17]
.LBB0_367:
	s_and_b64 vcc, exec, s[4:5]
	s_waitcnt lgkmcnt(0)
	v_mfma_f32_32x32x16_f16 v[18:33], v[152:155], v[156:159], v[18:33]
	s_cbranch_vccnz .LBB0_260
	v_mov_b32_e32 v131, v130
	v_mov_b32_e32 v132, v130
	v_mov_b32_e32 v133, v130
	s_nop 1
	v_mfma_f32_32x32x16_f16 v[2:17], v[130:133], v[156:159], v[2:17]
	s_branch .LBB0_260
